# static s_setprio 1 for waves 4-7 during GQA attention units (on top of v3)
# speedup vs baseline: 1.0130x; 1.0046x over previous
.LBB0_508:
	s_xor_b64 s[42:43], s[0:1], -1
	v_readlane_b32 s0, v251, 49
	v_mov_b32_e32 v42, v198
	s_add_i32 s0, s2, s0
	s_ashr_i32 s0, s0, 5
	v_readfirstlane_b32 s11, v42
	v_readlane_b32 s1, v251, 55
	s_ashr_i32 s10, s11, 6
	s_cmp_lt_u32 s10, 4
	s_cbranch_scc1 .Lgqa_prio_skip
	s_setprio 1
.Lgqa_prio_skip:
	s_add_i32 s2, s0, s1
	s_lshl_b32 s0, s10, 5
	s_ashr_i32 s1, s0, 31
	v_readlane_b32 s3, v251, 54
	s_add_u32 s46, s3, s0
	s_addc_u32 s47, 0, s1
	s_lshl_b64 s[0:1], s[46:47], 10
	v_readlane_b32 s4, v249, 58
	v_readlane_b32 s5, v249, 59
	s_add_u32 s3, s4, s0
	s_addc_u32 s4, s5, s1
	s_lshl_b32 s0, s2, 6
	s_ashr_i32 s1, s0, 31
	s_lshl_b64 s[44:45], s[0:1], 1
	s_add_u32 s6, s3, s44
	s_addc_u32 s7, s4, s45
	s_lshl_b32 s0, s2, 4
	s_andn2_b32 s0, s0, 63
	s_ashr_i32 s1, s0, 31
	s_lshl_b64 s[2:3], s[0:1], 1
	v_readlane_b32 s0, v251, 56
	s_add_u32 s4, s0, s2
	v_readlane_b32 s0, v251, 59
	v_and_b32_e32 v187, 63, v42
	s_addc_u32 s5, s0, s3
	v_readlane_b32 s0, v251, 60
	s_add_u32 s8, s0, s2
	v_readlane_b32 s0, v251, 63
	v_lshlrev_b32_e32 v0, 8, v187
	s_addc_u32 s9, s0, s3
	v_lshl_add_u64 v[2:3], s[4:5], 0, v[0:1]
	s_lshl_b32 s4, s10, 3
	s_ashr_i32 s5, s4, 31
	v_lshl_add_u64 v[190:191], s[4:5], 1, v[2:3]
	s_lshl_b32 s1, s10, 4
	v_bfe_u32 v2, v42, 2, 4
	v_and_or_b32 v2, s1, 48, v2
	v_lshlrev_b32_e32 v2, 8, v2
	v_mov_b32_e32 v3, v1
	s_ashr_i32 s1, s11, 3
	v_lshl_add_u64 v[2:3], s[8:9], 0, v[2:3]
	s_and_b32 s8, s1, 0xffffffe0
	s_and_b32 s0, s11, 0x3fffffc0
	s_ashr_i32 s9, s8, 31
	s_lshl_b32 s1, s10, 10
	v_lshlrev_b32_e32 v196, 3, v42
	s_cmp_lg_u32 0, -1
	v_lshl_add_u64 v[2:3], s[8:9], 1, v[2:3]
	v_and_b32_e32 v215, 24, v196
	s_cselect_b32 s8, 0, 0
	v_bfe_u32 v214, v42, 5, 1
	v_lshlrev_b32_e32 v4, 1, v215
	v_mov_b32_e32 v5, v1
	s_add_i32 s14, s1, s8
	s_mov_b32 s1, m0
	s_mov_b32 m0, s14
	s_nop 0
	global_load_lds_dwordx4 v[190:191], off
	s_mov_b32 m0, s1
	v_and_b32_e32 v197, 31, v42
	v_lshl_add_u64 v[188:189], v[2:3], 0, v[4:5]
	s_add_i32 s16, s14, 0x6000
	s_mov_b32 s1, m0
	s_mov_b32 m0, s16
	s_nop 0
	global_load_lds_dwordx4 v[188:189], off
	s_mov_b32 m0, s1
	s_mov_b64 s[22:23], 0x4000
	v_lshlrev_b32_e32 v218, 4, v214
	v_lshl_add_u64 v[2:3], v[190:191], 0, s[22:23]
	s_add_i32 s1, s14, 0x2000
	s_mov_b32 s8, m0
	s_mov_b32 m0, s1
	s_nop 0
	global_load_lds_dwordx4 v[2:3], off
	s_mov_b32 m0, s8
	v_lshl_or_b32 v10, v197, 10, v218
	global_load_dwordx4 v[142:145], v10, s[6:7]
	global_load_dwordx4 v[138:141], v10, s[6:7] offset:32
	global_load_dwordx4 v[130:133], v10, s[6:7] offset:64
	global_load_dwordx4 v[122:125], v10, s[6:7] offset:96
	v_mov_b32_e32 v2, v1
	v_mov_b32_e32 v3, v1
	v_mov_b32_e32 v4, v1
	v_mov_b32_e32 v6, v1
	v_mov_b32_e32 v7, v1
	v_mov_b32_e32 v8, v1
	v_mov_b32_e32 v9, v1
	v_mov_b32_e32 v10, v1
	v_mov_b32_e32 v11, v1
	v_mov_b32_e32 v12, v1
	v_mov_b32_e32 v13, v1
	v_mov_b32_e32 v14, v1
	v_mov_b32_e32 v15, v1
	v_mov_b32_e32 v16, v1
	v_mov_b32_e32 v17, v1
	v_lshlrev_b32_e32 v18, 10, v214
	v_lshlrev_b32_e32 v19, 4, v197
	v_add3_u32 v222, 0, v18, v19
	v_lshl_add_u64 v[18:19], v[190:191], 0, s[58:59]
	s_add_i32 s1, s14, 0x4000
	s_mov_b32 s6, m0
	s_mov_b32 m0, s1
	s_nop 0
	global_load_lds_dwordx4 v[18:19], off
	s_mov_b32 m0, s6
	s_waitcnt vmcnt(3) lgkmcnt(0)
	s_barrier
	ds_read_b128 v[34:37], v222
	ds_read_b128 v[38:41], v222 offset:512
	s_lshl_b32 s0, s0, 2
	s_mov_b64 s[6:7], 0xc000
	s_add_i32 s11, s0, 0
	v_mov_b32_e32 v223, 0
	s_mov_b32 s8, -1
	s_movk_i32 s12, 0x2000
	s_movk_i32 s9, 0x4000
	v_cmp_gt_u32_e64 s[40:41], 32, v187
	v_lshl_add_u32 v219, v197, 2, s11
	v_lshl_add_u64 v[192:193], v[188:189], 0, s[6:7]
	s_waitcnt vmcnt(3) lgkmcnt(1)
	v_mfma_f32_32x32x16_bf16 v[18:33], v[34:37], v[142:145], v[2:17]
	s_waitcnt lgkmcnt(0)
	v_mfma_f32_32x32x16_bf16 v[2:17], v[38:41], v[142:145], v[2:17]
	ds_read_b128 v[34:37], v222 offset:2048
	ds_read_b128 v[38:41], v222 offset:2560
	s_waitcnt vmcnt(2) lgkmcnt(1)
	v_mfma_f32_32x32x16_bf16 v[18:33], v[34:37], v[138:141], v[18:33]
	s_waitcnt lgkmcnt(0)
	v_mfma_f32_32x32x16_bf16 v[2:17], v[38:41], v[138:141], v[2:17]
	ds_read_b128 v[34:37], v222 offset:4096
	ds_read_b128 v[38:41], v222 offset:4608
	s_waitcnt vmcnt(1) lgkmcnt(1)
	v_mfma_f32_32x32x16_bf16 v[18:33], v[34:37], v[130:133], v[18:33]
	ds_read_b128 v[34:37], v222 offset:6144
	s_waitcnt lgkmcnt(1)
	v_mfma_f32_32x32x16_bf16 v[2:17], v[38:41], v[130:133], v[2:17]
	ds_read_b128 v[38:41], v222 offset:6656
	s_waitcnt vmcnt(0) lgkmcnt(1)
	v_mfma_f32_32x32x16_bf16 v[18:33], v[34:37], v[122:125], v[18:33]
	v_lshlrev_b32_e32 v34, 1, v42
	v_lshlrev_b32_e32 v35, 4, v42
	v_and_b32_e32 v217, 32, v34
	v_and_b32_e32 v34, 0xc0, v35
	v_lshl_or_b32 v216, v214, 8, v34
	v_add_u32_e32 v34, 0, v217
	v_add3_u32 v220, v34, v215, v216
	s_waitcnt lgkmcnt(0)
	v_mfma_f32_32x32x16_bf16 v[2:17], v[38:41], v[122:125], v[2:17]
	s_nop 15
	s_nop 7
	s_nop 0
	v_max3_f32 v34, v18, v19, v2
	v_max3_f32 v35, v20, v21, v3
	s_nop 0
	v_max3_f32 v34, v34, v4, v5
	v_max3_f32 v35, v35, v24, v25
	s_nop 0
	v_max3_f32 v34, v34, v22, v23
	v_max3_f32 v35, v35, v8, v9
	s_nop 0
	v_max3_f32 v34, v34, v6, v7
	v_max3_f32 v35, v35, v28, v29
	s_nop 0
	v_max3_f32 v34, v34, v26, v27
	v_max3_f32 v35, v35, v12, v13
	s_nop 0
	v_max3_f32 v34, v34, v10, v11
	v_max3_f32 v35, v35, v32, v33
	s_nop 0
	v_max3_f32 v34, v34, v30, v31
	v_max3_f32 v35, v35, v16, v17
	s_nop 0
	v_max3_f32 v34, v34, v14, v15
	s_nop 0
	v_max_f32_e32 v34, v34, v35
	s_nop 0
	v_mov_b32_e32 v35, v34
	s_nop 1
	v_permlane32_swap_b32_e32 v34, v35
	v_max_f32_e32 v34, v34, v35
	s_nop 0
	v_add_f32_e32 v221, v1, v34
	v_sub_f32_e32 v18, v18, v34
	v_sub_f32_e32 v2, v2, v34
	v_sub_f32_e32 v19, v19, v34
	v_sub_f32_e32 v3, v3, v34
	v_sub_f32_e32 v20, v20, v34
	v_sub_f32_e32 v4, v4, v34
	v_sub_f32_e32 v21, v21, v34
	v_sub_f32_e32 v5, v5, v34
	v_sub_f32_e32 v22, v22, v34
	v_sub_f32_e32 v6, v6, v34
	v_sub_f32_e32 v23, v23, v34
	v_sub_f32_e32 v7, v7, v34
	v_sub_f32_e32 v24, v24, v34
	v_sub_f32_e32 v8, v8, v34
	v_sub_f32_e32 v25, v25, v34
	v_sub_f32_e32 v9, v9, v34
	v_sub_f32_e32 v26, v26, v34
	v_sub_f32_e32 v10, v10, v34
	v_sub_f32_e32 v27, v27, v34
	v_sub_f32_e32 v11, v11, v34
	v_sub_f32_e32 v28, v28, v34
	v_sub_f32_e32 v12, v12, v34
	v_sub_f32_e32 v29, v29, v34
	v_sub_f32_e32 v13, v13, v34
	v_sub_f32_e32 v30, v30, v34
	v_sub_f32_e32 v14, v14, v34
	v_sub_f32_e32 v31, v31, v34
	v_sub_f32_e32 v15, v15, v34
	v_sub_f32_e32 v32, v32, v34
	v_sub_f32_e32 v16, v16, v34
	v_sub_f32_e32 v33, v33, v34
	v_sub_f32_e32 v17, v17, v34
	s_nop 0
	v_xor_b32_e32 v34, 0x80000000, v221
	v_mov_b32_e32 v35, v34
	v_mov_b32_e32 v36, v34
	v_mov_b32_e32 v37, v34
	v_mov_b32_e32 v38, v34
	v_mov_b32_e32 v39, v34
	v_mov_b32_e32 v40, v34
	v_mov_b32_e32 v41, v34
	v_mov_b32_e32 v42, v34
	v_mov_b32_e32 v43, v34
	v_mov_b32_e32 v44, v34
	v_mov_b32_e32 v45, v34
	v_mov_b32_e32 v46, v34
	v_mov_b32_e32 v47, v34
	v_mov_b32_e32 v48, v34
	v_mov_b32_e32 v49, v34
	s_waitcnt vmcnt(0) lgkmcnt(0)
	s_barrier
	v_exp_f32_e32 v50, v2
	v_exp_f32_e32 v51, v3
	v_lshl_add_u64 v[2:3], v[190:191], 0, s[6:7]
	s_mov_b32 s0, m0
	s_mov_b32 m0, s14
	s_nop 0
	global_load_lds_dwordx4 v[2:3], off
	s_mov_b32 m0, s0
	v_lshl_add_u64 v[2:3], v[188:189], 0, s[22:23]
	s_add_i32 s0, s14, 0x8000
	s_mov_b32 s1, m0
	s_mov_b32 m0, s0
	s_nop 0
	global_load_lds_dwordx4 v[2:3], off
	s_mov_b32 m0, s1
	ds_read_b128 v[174:177], v222 offset:8192
	ds_read_b128 v[170:173], v222 offset:8704
	ds_read_b128 v[166:169], v222 offset:10240
	ds_read_b128 v[162:165], v222 offset:10752
	ds_read_b128 v[158:161], v222 offset:12288
	ds_read_b128 v[154:157], v222 offset:12800
	ds_read_b128 v[150:153], v222 offset:14336
	ds_read_b128 v[146:149], v222 offset:14848
	v_exp_f32_e32 v66, v18
	v_exp_f32_e32 v67, v19
	v_exp_f32_e32 v68, v20
	v_exp_f32_e32 v69, v21
	v_exp_f32_e32 v70, v22
	v_exp_f32_e32 v71, v23
	v_exp_f32_e32 v72, v24
	v_exp_f32_e32 v73, v25
	v_exp_f32_e32 v74, v26
	v_exp_f32_e32 v75, v27
	v_exp_f32_e32 v76, v28
	v_exp_f32_e32 v77, v29
	v_exp_f32_e32 v78, v30
	v_exp_f32_e32 v79, v31
	v_exp_f32_e32 v80, v32
	v_exp_f32_e32 v81, v33
	v_exp_f32_e32 v52, v4
	v_exp_f32_e32 v53, v5
	v_exp_f32_e32 v54, v6
	v_exp_f32_e32 v55, v7
	v_exp_f32_e32 v56, v8
	v_exp_f32_e32 v57, v9
	v_exp_f32_e32 v58, v10
	v_exp_f32_e32 v59, v11
	v_exp_f32_e32 v60, v12
	v_exp_f32_e32 v61, v13
	v_exp_f32_e32 v62, v14
	v_exp_f32_e32 v63, v15
	v_exp_f32_e32 v64, v16
	v_exp_f32_e32 v65, v17
	s_waitcnt vmcnt(2) lgkmcnt(0)
	s_barrier
	s_mov_b64 s[0:1], 0x14000
	v_lshl_add_u64 v[194:195], v[190:191], 0, s[0:1]
	s_mov_b32 s0, 0
	v_mov_b32_e32 v2, 0
	v_mov_b32_e32 v3, v223
	v_mov_b32_e32 v4, v223
	v_mov_b32_e32 v5, v223
	v_mov_b32_e32 v6, v223
	v_mov_b32_e32 v7, v223
	v_mov_b32_e32 v8, v223
	v_mov_b32_e32 v9, v223
	v_mov_b32_e32 v10, v223
	v_mov_b32_e32 v11, v223
	v_mov_b32_e32 v12, v223
	v_mov_b32_e32 v13, v223
	v_mov_b32_e32 v14, v223
	v_mov_b32_e32 v15, v223
	v_mov_b32_e32 v16, v223
	v_mov_b32_e32 v17, v223
	v_mov_b32_e32 v18, 0
	v_mov_b32_e32 v19, v223
	v_mov_b32_e32 v20, v223
	v_mov_b32_e32 v21, v223
	v_mov_b32_e32 v22, v223
	v_mov_b32_e32 v23, v223
	v_mov_b32_e32 v24, v223
	v_mov_b32_e32 v25, v223
	v_mov_b32_e32 v26, v223
	v_mov_b32_e32 v27, v223
	v_mov_b32_e32 v28, v223
	v_mov_b32_e32 v29, v223
	v_mov_b32_e32 v30, v223
	v_mov_b32_e32 v31, v223
	v_mov_b32_e32 v32, v223
	v_mov_b32_e32 v33, v223
	s_mov_b64 s[22:23], 0x200000

.LBB0_625:
	s_setprio 0
	v_readlane_b32 s0, v254, 51
	v_readlane_b32 s1, v254, 52
	s_andn2_b64 vcc, exec, s[0:1]
	s_mov_b32 s4, s80
	s_cbranch_vccz .LBB0_630
